# v009 + L1 invalidate issued before the barrier spin instead of after (isolating this change)
# baseline (speedup 1.0000x reference)
; __device__ __forceinline__ unsigned xb_ld(unsigned* p)              { return __hip_atomic_load(p, __ATOMIC_RELAXED, __HIP_MEMORY_SCOPE_AGENT); }
; #define XB_SPIN(cond, bar) do { unsigned _sp = 0; while (cond) { __builtin_amdgcn_s_sleep(1); \
;     if ((++_sp & 255u) == 0u) { if (xb_ld(&(bar)[XB_TMO])) break; if (_sp > XB_SPIN_CAP) { atomicAdd(&(bar)[XB_TMO], 1u); break; } } } } while (0)
; __device__ __forceinline__ void xcd_local_barrier(const XcdBarrier& b) {
;     ...
;         else XB_SPIN(xb_ld(&bar[XL_GEN(x_)]) == gen, bar);
;         __builtin_amdgcn_fence(__ATOMIC_ACQUIRE, "agent");
;         asm volatile("s_waitcnt vmcnt(0)" ::: "memory");
;     }
;     __syncthreads();
.LBB0_285:
	s_or_b64 exec, exec, s[2:3]
	s_waitcnt vmcnt(0)
	s_waitcnt vmcnt(0)

; __device__ __forceinline__ unsigned xb_ld(unsigned* p)              { return __hip_atomic_load(p, __ATOMIC_RELAXED, __HIP_MEMORY_SCOPE_AGENT); }
; __device__ __forceinline__ unsigned xb_add(unsigned* p, unsigned v) { return __hip_atomic_fetch_add(p, v, __ATOMIC_RELAXED, __HIP_MEMORY_SCOPE_AGENT); }
; #define XB_SPIN(cond, bar) do { unsigned _sp = 0; while (cond) { __builtin_amdgcn_s_sleep(1); \
;     if ((++_sp & 255u) == 0u) { if (xb_ld(&(bar)[XB_TMO])) break; if (_sp > XB_SPIN_CAP) { atomicAdd(&(bar)[XB_TMO], 1u); break; } } } } while (0)
; __device__ __forceinline__ void xcd_barrier(const XcdBarrier& b) {
;     ...
;         const unsigned old = xb_add(&bar[XB_XSUB(bx_)], 1u);
;         const unsigned gen = old / nloc;
;         if (old + 1u == (gen + 1u) * nloc) {
;             __builtin_amdgcn_fence(__ATOMIC_RELEASE, "agent");
;             asm volatile("s_waitcnt vmcnt(0)" ::: "memory");
;             const unsigned og = xb_add(&bar[XB_TOP], 1u);
;             const unsigned tg = og / nx;
;             if (og + 1u == (tg + 1u) * nx) xb_add(&bar[XB_TOPGEN], 1u);
;             else XB_SPIN(xb_ld(&bar[XB_TOPGEN]) == tg, bar);
;             __builtin_amdgcn_fence(__ATOMIC_ACQUIRE, "agent");
;             xb_add(&bar[XB_XGEN(bx_)], 1u);
;             asm volatile("s_waitcnt vmcnt(0)" ::: "memory");
;         } else {
;             XB_SPIN(xb_ld(&bar[XB_XGEN(bx_)]) == gen, bar);
.LBB0_674:
	s_or_b64 exec, exec, s[6:7]
	v_cvt_f32_u32_e32 v5, v3
	s_waitcnt vmcnt(0)
	v_readfirstlane_b32 s4, v4
	v_sub_u32_e32 v4, 0, v3
	v_rcp_iflag_f32_e32 v5, v5
	v_add_u32_e32 v6, s4, v0
	v_mul_f32_e32 v5, 0x4f7ffffe, v5
	v_cvt_u32_f32_e32 v5, v5
	v_mul_lo_u32 v0, v4, v5
	v_mul_hi_u32 v0, v5, v0
	v_add_u32_e32 v0, v5, v0
	v_mul_hi_u32 v0, v6, v0
	v_mul_lo_u32 v4, v0, v3
	v_sub_u32_e32 v4, v6, v4
	v_add_u32_e32 v5, 1, v0
	v_cmp_ge_u32_e32 vcc, v4, v3
	s_nop 1
	v_cndmask_b32_e32 v0, v0, v5, vcc
	v_sub_u32_e32 v5, v4, v3
	v_cndmask_b32_e32 v4, v4, v5, vcc
	v_add_u32_e32 v5, 1, v0
	v_cmp_ge_u32_e32 vcc, v4, v3
	v_add_u32_e32 v4, 1, v6
	s_nop 0
	v_cndmask_b32_e32 v0, v0, v5, vcc
	v_mul_lo_u32 v5, v3, v0
	v_add_u32_e32 v3, v5, v3
	v_cmp_ne_u32_e32 vcc, v4, v3
	s_and_saveexec_b64 s[4:5], vcc
	s_xor_b64 s[4:5], exec, s[4:5]
	s_cbranch_execz .LBB0_688
	s_waitcnt lgkmcnt(0)
	buffer_inv sc1
	global_load_dword v2, v241, s[2:3] offset:1024 sc1
	s_add_u32 s8, s2, 0x2400
	s_addc_u32 s9, s3, 0
	s_waitcnt vmcnt(0)
	v_cmp_eq_u32_e32 vcc, v2, v0
	s_and_saveexec_b64 s[6:7], vcc
	s_cbranch_execz .LBB0_687
	s_mov_b32 s12, 1
	s_mov_b64 s[10:11], 0
	s_branch .LBB0_678

; __device__ __forceinline__ unsigned xb_ld(unsigned* p)              { return __hip_atomic_load(p, __ATOMIC_RELAXED, __HIP_MEMORY_SCOPE_AGENT); }
; #define XB_SPIN(cond, bar) do { unsigned _sp = 0; while (cond) { __builtin_amdgcn_s_sleep(1); \
;     if ((++_sp & 255u) == 0u) { if (xb_ld(&(bar)[XB_TMO])) break; if (_sp > XB_SPIN_CAP) { atomicAdd(&(bar)[XB_TMO], 1u); break; } } } } while (0)
; __device__ __forceinline__ void xcd_barrier(const XcdBarrier& b) {
;     ...
;             XB_SPIN(xb_ld(&bar[XB_XGEN(bx_)]) == gen, bar);
;             __builtin_amdgcn_fence(__ATOMIC_ACQUIRE, "agent");
;             asm volatile("s_waitcnt vmcnt(0)" ::: "memory");
;         }
.LBB0_687:
	s_or_b64 exec, exec, s[6:7]
	s_waitcnt vmcnt(0)
	s_waitcnt vmcnt(0)

; __device__ __forceinline__ unsigned xb_ld(unsigned* p)              { return __hip_atomic_load(p, __ATOMIC_RELAXED, __HIP_MEMORY_SCOPE_AGENT); }
; __device__ __forceinline__ unsigned xb_add(unsigned* p, unsigned v) { return __hip_atomic_fetch_add(p, v, __ATOMIC_RELAXED, __HIP_MEMORY_SCOPE_AGENT); }
; __device__ __forceinline__ unsigned xb_xcc_id() { return (unsigned)__builtin_amdgcn_s_getreg((3 << 11) | 20) & 0xFu; }
; #define XB_SPIN(cond, bar) do { unsigned _sp = 0; while (cond) { __builtin_amdgcn_s_sleep(1); \
;     if ((++_sp & 255u) == 0u) { if (xb_ld(&(bar)[XB_TMO])) break; if (_sp > XB_SPIN_CAP) { atomicAdd(&(bar)[XB_TMO], 1u); break; } } } } while (0)
; __device__ __forceinline__ void xcd_local_barrier(const XcdBarrier& b) {
;     asm volatile("s_waitcnt vmcnt(0)" ::: "memory");
;     __syncthreads();
;     if (threadIdx.x == 0) {
;         unsigned* bar = b.bar; const unsigned x_ = xb_xcc_id();
;         __builtin_amdgcn_s_waitcnt(0);
;         const unsigned nloc = b.st[0];
;         const unsigned old = xb_add(&bar[XL_SUB(x_)], 1u);
;         const unsigned gen = old / nloc;
;         if (old + 1u == (gen + 1u) * nloc) xb_add(&bar[XL_GEN(x_)], 1u);
;         else XB_SPIN(xb_ld(&bar[XL_GEN(x_)]) == gen, bar);
.LBB0_709:
	s_and_b64 vcc, exec, s[0:1]
	s_cbranch_vccz .LBB0_287
	s_waitcnt vmcnt(0)
	s_waitcnt vmcnt(0) lgkmcnt(0)
	s_barrier
	s_mov_b64 s[0:1], exec
	v_readlane_b32 s2, v254, 2
	v_readlane_b32 s3, v254, 3
	s_and_b64 s[2:3], s[0:1], s[2:3]
	s_mov_b64 exec, s[2:3]
	s_cbranch_execz .LBB0_286
	v_readlane_b32 s3, v255, 0
	s_getreg_b32 s2, hwreg(HW_REG_XCC_ID, 0, 4)
	s_waitcnt vmcnt(0) expcnt(0) lgkmcnt(0)
	buffer_inv sc1
	v_mov_b32_e32 v0, s3
	ds_read_b32 v2, v0
	s_mov_b64 s[4:5], exec
	s_lshl_b32 s2, s2, 8
	s_and_b32 s2, s2, 0xf00
	v_readlane_b32 s6, v254, 0
	v_mbcnt_lo_u32_b32 v0, s4, 0
	v_readlane_b32 s7, v254, 1
	s_add_u32 s2, s6, s2
	v_mbcnt_hi_u32_b32 v0, s5, v0
	s_addc_u32 s3, s7, 0
	v_cmp_eq_u32_e32 vcc, 0, v0
	s_and_saveexec_b64 s[6:7], vcc
	v_readlane_b32 s26, v254, 4
	v_readlane_b32 s27, v254, 5
	s_cbranch_execz .LBB0_713
	s_bcnt1_i32_b64 s4, s[4:5]
	v_mov_b32_e32 v3, s4
	v_mov_b32_e32 v4, 0x4000
	global_atomic_add v3, v4, v3, s[2:3] sc0
